# GEMM STORE/RELU2/UG epilogues: the eight per-row scale loads issued together (was load+wait per 16-row group)
# baseline (speedup 1.0000x reference)
.LBB0_125:
	v_lshrrev_b32_e32 v136, 4, v194
	s_and_b64 vcc, exec, vcc
	s_cbranch_vccz .LBB0_130
	s_cmp_gt_i32 s68, 2
	s_mov_b64 s[10:11], -1
	s_cbranch_scc0 .LBB0_128
	v_ashrrev_i32_e32 v163, 31, v162
	v_lshl_add_u64 v[132:133], v[162:163], 2, s[86:87]
	global_load_dword v142, v[132:133], off
	global_load_dword v244, v[132:133], off offset:64
	global_load_dword v245, v[132:133], off offset:128
	global_load_dword v246, v[132:133], off offset:192
	global_load_dword v247, v[132:133], off offset:512
	global_load_dword v248, v[132:133], off offset:576
	global_load_dword v249, v[132:133], off offset:640
	global_load_dword v250, v[132:133], off offset:704
	s_lshl_b32 s10, s35, 4
	s_lshl_b32 s11, s36, 1
	s_or_b32 s10, s11, s10
	v_lshrrev_b32_e32 v0, 1, v192
	v_or_b32_e32 v137, s10, v0
	v_lshlrev_b32_e32 v0, 4, v136
	v_and_b32_e32 v0, 16, v0
	v_lshl_add_u64 v[130:131], s[98:99], 0, v[0:1]
	s_ashr_i32 s40, s40, 5
	v_lshlrev_b32_e32 v0, 5, v193
	v_lshlrev_b32_e32 v137, 10, v137
	v_lshl_add_u64 v[134:135], v[130:131], 0, v[0:1]
	v_add_u32_e32 v163, s40, v137
	v_lshlrev_b32_e32 v0, 5, v162
	s_waitcnt vmcnt(0)
	v_pk_mul_f32 v[140:141], v[128:129], v[142:143] op_sel_hi:[1,0]
	v_pk_mul_f32 v[138:139], v[126:127], v[142:143] op_sel_hi:[1,0]
	v_pk_mul_f32 v[144:145], v[124:125], v[142:143] op_sel_hi:[1,0]
	v_pk_mul_f32 v[146:147], v[122:123], v[142:143] op_sel_hi:[1,0]
	v_cvt_pk_bf16_f32 v138, v138, v139
	v_cvt_pk_bf16_f32 v139, v140, v141
	v_cvt_pk_bf16_f32 v141, v144, v145
	v_mad_i64_i32 v[144:145], s[10:11], v163, s97, v[134:135]
	v_cvt_pk_bf16_f32 v140, v146, v147
	global_store_dwordx4 v[144:145], v[138:141], off
	v_pk_mul_f32 v[144:145], v[116:117], v[142:143] op_sel_hi:[1,0]
	s_nop 0
	v_pk_mul_f32 v[138:139], v[120:121], v[142:143] op_sel_hi:[1,0]
	v_pk_mul_f32 v[140:141], v[118:119], v[142:143] op_sel_hi:[1,0]
	v_pk_mul_f32 v[142:143], v[114:115], v[142:143] op_sel_hi:[1,0]
	v_cvt_pk_bf16_f32 v140, v140, v141
	v_cvt_pk_bf16_f32 v141, v138, v139
	v_or_b32_e32 v138, 0x2000, v137
	v_add_u32_e32 v139, s40, v138
	v_cvt_pk_bf16_f32 v142, v142, v143
	v_cvt_pk_bf16_f32 v143, v144, v145
	v_mad_i64_i32 v[144:145], s[10:11], v139, s97, v[134:135]
	global_store_dwordx4 v[144:145], v[140:143], off
	s_nop 0
	s_movk_i32 s10, 0x3e0
	v_bitop3_b32 v0, v0, s10, v181 bitop3:0xc8
	v_lshl_add_u64 v[146:147], v[130:131], 0, v[0:1]
	s_nop 1
	v_mov_b32_e32 v144, v244
	s_nop 0
	v_pk_mul_f32 v[142:143], v[112:113], v[144:145] op_sel_hi:[1,0]
	v_pk_mul_f32 v[140:141], v[110:111], v[144:145] op_sel_hi:[1,0]
	v_pk_mul_f32 v[148:149], v[108:109], v[144:145] op_sel_hi:[1,0]
	v_pk_mul_f32 v[164:165], v[106:107], v[144:145] op_sel_hi:[1,0]
	v_cvt_pk_bf16_f32 v140, v140, v141
	v_cvt_pk_bf16_f32 v141, v142, v143
	v_cvt_pk_bf16_f32 v143, v148, v149
	v_mad_i64_i32 v[148:149], s[10:11], v163, s97, v[146:147]
	v_cvt_pk_bf16_f32 v142, v164, v165
	global_store_dwordx4 v[148:149], v[140:143], off
	v_pk_mul_f32 v[148:149], v[100:101], v[144:145] op_sel_hi:[1,0]
	s_nop 0
	v_pk_mul_f32 v[142:143], v[104:105], v[144:145] op_sel_hi:[1,0]
	v_pk_mul_f32 v[140:141], v[102:103], v[144:145] op_sel_hi:[1,0]
	v_pk_mul_f32 v[144:145], v[98:99], v[144:145] op_sel_hi:[1,0]
	v_cvt_pk_bf16_f32 v140, v140, v141
	v_cvt_pk_bf16_f32 v141, v142, v143
	v_cvt_pk_bf16_f32 v143, v148, v149
	s_nop 0
	v_cvt_pk_bf16_f32 v142, v144, v145
	v_mad_i64_i32 v[144:145], s[10:11], v139, s97, v[146:147]
	global_store_dwordx4 v[144:145], v[140:143], off
	s_nop 0
	v_ashrrev_i32_e32 v139, 5, v162
	v_or_b32_e32 v139, 1, v139
	s_nop 1
	v_mov_b32_e32 v0, v245
	s_nop 0
	v_pk_mul_f32 v[142:143], v[96:97], v[0:1] op_sel_hi:[1,0]
	v_pk_mul_f32 v[140:141], v[94:95], v[0:1] op_sel_hi:[1,0]
	v_pk_mul_f32 v[144:145], v[92:93], v[0:1] op_sel_hi:[1,0]
	v_cvt_pk_bf16_f32 v140, v140, v141
	v_cvt_pk_bf16_f32 v141, v142, v143
	v_pk_mul_f32 v[146:147], v[90:91], v[0:1] op_sel_hi:[1,0]
	v_cvt_pk_bf16_f32 v143, v144, v145
	v_add_u32_e32 v144, v137, v139
	v_cvt_pk_bf16_f32 v142, v146, v147
	v_mad_i64_i32 v[144:145], s[10:11], v144, s97, v[134:135]
	global_store_dwordx4 v[144:145], v[140:143], off
	v_pk_mul_f32 v[144:145], v[84:85], v[0:1] op_sel_hi:[1,0]
	v_pk_mul_f32 v[146:147], v[82:83], v[0:1] op_sel_hi:[1,0]
	v_pk_mul_f32 v[142:143], v[88:89], v[0:1] op_sel_hi:[1,0]
	v_pk_mul_f32 v[140:141], v[86:87], v[0:1] op_sel_hi:[1,0]
	v_add_u32_e32 v0, v138, v139
	v_cvt_pk_bf16_f32 v140, v140, v141
	v_cvt_pk_bf16_f32 v141, v142, v143
	v_cvt_pk_bf16_f32 v143, v144, v145
	v_mad_i64_i32 v[144:145], s[10:11], v0, s97, v[134:135]
	v_cvt_pk_bf16_f32 v142, v146, v147
	global_store_dwordx4 v[144:145], v[140:143], off
	s_nop 0
	v_or_b32_e32 v0, 48, v162
	v_ashrrev_i32_e32 v139, 5, v0
	v_lshlrev_b32_e32 v0, 5, v0
	v_and_b32_e32 v0, 0x3e0, v0
	v_lshl_add_u64 v[146:147], v[130:131], 0, v[0:1]
	v_add_u32_e32 v0, v137, v139
	s_nop 1
	v_mov_b32_e32 v144, v246
	s_nop 0
	v_pk_mul_f32 v[142:143], v[80:81], v[144:145] op_sel_hi:[1,0]
	v_pk_mul_f32 v[140:141], v[78:79], v[144:145] op_sel_hi:[1,0]
	v_pk_mul_f32 v[148:149], v[76:77], v[144:145] op_sel_hi:[1,0]
	v_pk_mul_f32 v[164:165], v[74:75], v[144:145] op_sel_hi:[1,0]
	v_cvt_pk_bf16_f32 v140, v140, v141
	v_cvt_pk_bf16_f32 v141, v142, v143
	v_cvt_pk_bf16_f32 v143, v148, v149
	v_mad_i64_i32 v[148:149], s[10:11], v0, s97, v[146:147]
	v_cvt_pk_bf16_f32 v142, v164, v165
	global_store_dwordx4 v[148:149], v[140:143], off
	v_pk_mul_f32 v[148:149], v[68:69], v[144:145] op_sel_hi:[1,0]
	v_add_u32_e32 v0, v138, v139
	v_pk_mul_f32 v[142:143], v[72:73], v[144:145] op_sel_hi:[1,0]
	v_pk_mul_f32 v[140:141], v[70:71], v[144:145] op_sel_hi:[1,0]
	v_pk_mul_f32 v[144:145], v[66:67], v[144:145] op_sel_hi:[1,0]
	v_cvt_pk_bf16_f32 v140, v140, v141
	v_cvt_pk_bf16_f32 v141, v142, v143
	v_cvt_pk_bf16_f32 v143, v148, v149
	v_add_u32_e32 v139, 0x80, v162
	v_cvt_pk_bf16_f32 v142, v144, v145
	v_mad_i64_i32 v[144:145], s[10:11], v0, s97, v[146:147]
	global_store_dwordx4 v[144:145], v[140:143], off
	s_nop 0
	v_ashrrev_i32_e32 v139, 5, v139
	s_nop 1
	v_mov_b32_e32 v0, v247
	s_nop 0
	v_pk_mul_f32 v[142:143], v[64:65], v[0:1] op_sel_hi:[1,0]
	v_pk_mul_f32 v[140:141], v[62:63], v[0:1] op_sel_hi:[1,0]
	v_pk_mul_f32 v[144:145], v[60:61], v[0:1] op_sel_hi:[1,0]
	v_cvt_pk_bf16_f32 v140, v140, v141
	v_cvt_pk_bf16_f32 v141, v142, v143
	v_pk_mul_f32 v[146:147], v[58:59], v[0:1] op_sel_hi:[1,0]
	v_cvt_pk_bf16_f32 v143, v144, v145
	v_add_u32_e32 v144, v137, v139
	v_cvt_pk_bf16_f32 v142, v146, v147
	v_mad_i64_i32 v[144:145], s[10:11], v144, s97, v[134:135]
	global_store_dwordx4 v[144:145], v[140:143], off
	v_pk_mul_f32 v[144:145], v[52:53], v[0:1] op_sel_hi:[1,0]
	v_pk_mul_f32 v[146:147], v[50:51], v[0:1] op_sel_hi:[1,0]
	v_pk_mul_f32 v[142:143], v[56:57], v[0:1] op_sel_hi:[1,0]
	v_pk_mul_f32 v[140:141], v[54:55], v[0:1] op_sel_hi:[1,0]
	v_add_u32_e32 v0, v138, v139
	v_cvt_pk_bf16_f32 v140, v140, v141
	v_cvt_pk_bf16_f32 v141, v142, v143
	v_cvt_pk_bf16_f32 v143, v144, v145
	v_mad_i64_i32 v[144:145], s[10:11], v0, s97, v[134:135]
	v_cvt_pk_bf16_f32 v142, v146, v147
	global_store_dwordx4 v[144:145], v[140:143], off
	s_nop 0
	v_add_u32_e32 v0, 0x90, v162
	v_ashrrev_i32_e32 v139, 5, v0
	v_lshlrev_b32_e32 v0, 5, v0
	v_and_b32_e32 v0, 0x3e0, v0
	v_lshl_add_u64 v[146:147], v[130:131], 0, v[0:1]
	v_add_u32_e32 v0, v137, v139
	s_nop 1
	v_mov_b32_e32 v144, v248
	s_nop 0
	v_pk_mul_f32 v[142:143], v[48:49], v[144:145] op_sel_hi:[1,0]
	v_pk_mul_f32 v[140:141], v[46:47], v[144:145] op_sel_hi:[1,0]
	v_pk_mul_f32 v[148:149], v[44:45], v[144:145] op_sel_hi:[1,0]
	v_pk_mul_f32 v[164:165], v[42:43], v[144:145] op_sel_hi:[1,0]
	v_cvt_pk_bf16_f32 v140, v140, v141
	v_cvt_pk_bf16_f32 v141, v142, v143
	v_cvt_pk_bf16_f32 v143, v148, v149
	v_mad_i64_i32 v[148:149], s[10:11], v0, s97, v[146:147]
	v_cvt_pk_bf16_f32 v142, v164, v165
	global_store_dwordx4 v[148:149], v[140:143], off
	v_pk_mul_f32 v[148:149], v[36:37], v[144:145] op_sel_hi:[1,0]
	v_add_u32_e32 v0, v138, v139
	v_pk_mul_f32 v[142:143], v[40:41], v[144:145] op_sel_hi:[1,0]
	v_pk_mul_f32 v[140:141], v[38:39], v[144:145] op_sel_hi:[1,0]
	v_pk_mul_f32 v[144:145], v[34:35], v[144:145] op_sel_hi:[1,0]
	v_cvt_pk_bf16_f32 v140, v140, v141
	v_cvt_pk_bf16_f32 v141, v142, v143
	v_cvt_pk_bf16_f32 v143, v148, v149
	v_add_u32_e32 v139, 0xa0, v162
	v_cvt_pk_bf16_f32 v142, v144, v145
	v_mad_i64_i32 v[144:145], s[10:11], v0, s97, v[146:147]
	global_store_dwordx4 v[144:145], v[140:143], off
	s_nop 0
	v_ashrrev_i32_e32 v139, 5, v139
	s_nop 1
	v_mov_b32_e32 v0, v249
	s_nop 0
	v_pk_mul_f32 v[142:143], v[32:33], v[0:1] op_sel_hi:[1,0]
	v_pk_mul_f32 v[140:141], v[30:31], v[0:1] op_sel_hi:[1,0]
	v_pk_mul_f32 v[144:145], v[28:29], v[0:1] op_sel_hi:[1,0]
	v_cvt_pk_bf16_f32 v140, v140, v141
	v_cvt_pk_bf16_f32 v141, v142, v143
	v_pk_mul_f32 v[146:147], v[26:27], v[0:1] op_sel_hi:[1,0]
	v_cvt_pk_bf16_f32 v143, v144, v145
	v_add_u32_e32 v144, v137, v139
	v_cvt_pk_bf16_f32 v142, v146, v147
	v_mad_i64_i32 v[144:145], s[10:11], v144, s97, v[134:135]
	global_store_dwordx4 v[144:145], v[140:143], off
	v_pk_mul_f32 v[144:145], v[20:21], v[0:1] op_sel_hi:[1,0]
	v_pk_mul_f32 v[146:147], v[18:19], v[0:1] op_sel_hi:[1,0]
	v_pk_mul_f32 v[142:143], v[24:25], v[0:1] op_sel_hi:[1,0]
	v_pk_mul_f32 v[140:141], v[22:23], v[0:1] op_sel_hi:[1,0]
	v_add_u32_e32 v0, v138, v139
	v_mad_i64_i32 v[134:135], s[10:11], v0, s97, v[134:135]
	v_cvt_pk_bf16_f32 v140, v140, v141
	v_cvt_pk_bf16_f32 v141, v142, v143
	v_cvt_pk_bf16_f32 v142, v146, v147
	v_cvt_pk_bf16_f32 v143, v144, v145
	global_store_dwordx4 v[134:135], v[140:143], off
	s_nop 0
	v_add_u32_e32 v0, 0xb0, v162
	v_ashrrev_i32_e32 v139, 5, v0
	v_lshlrev_b32_e32 v0, 5, v0
	v_and_b32_e32 v0, 0x3e0, v0
	v_lshl_add_u64 v[140:141], v[130:131], 0, v[0:1]
	v_add_u32_e32 v0, v137, v139
	s_nop 1
	v_mov_b32_e32 v134, v250
	s_nop 0
	v_pk_mul_f32 v[132:133], v[16:17], v[134:135] op_sel_hi:[1,0]
	v_pk_mul_f32 v[130:131], v[14:15], v[134:135] op_sel_hi:[1,0]
	v_pk_mul_f32 v[142:143], v[12:13], v[134:135] op_sel_hi:[1,0]
	v_pk_mul_f32 v[144:145], v[10:11], v[134:135] op_sel_hi:[1,0]
	v_cvt_pk_bf16_f32 v130, v130, v131
	v_cvt_pk_bf16_f32 v131, v132, v133
	v_cvt_pk_bf16_f32 v133, v142, v143
	v_mad_i64_i32 v[142:143], s[10:11], v0, s97, v[140:141]
	v_cvt_pk_bf16_f32 v132, v144, v145
	global_store_dwordx4 v[142:143], v[130:133], off
	v_pk_mul_f32 v[142:143], v[4:5], v[134:135] op_sel_hi:[1,0]
	v_add_u32_e32 v0, v138, v139
	v_pk_mul_f32 v[132:133], v[8:9], v[134:135] op_sel_hi:[1,0]
	v_pk_mul_f32 v[130:131], v[6:7], v[134:135] op_sel_hi:[1,0]
	v_pk_mul_f32 v[134:135], v[2:3], v[134:135] op_sel_hi:[1,0]
	v_cvt_pk_bf16_f32 v130, v130, v131
	v_cvt_pk_bf16_f32 v131, v132, v133
	v_cvt_pk_bf16_f32 v133, v142, v143
	s_nop 0
	v_cvt_pk_bf16_f32 v132, v134, v135
	v_mad_i64_i32 v[134:135], s[10:11], v0, s97, v[140:141]
	global_store_dwordx4 v[134:135], v[130:133], off
	s_mov_b64 s[10:11], 0

.LBB0_135:
	v_ashrrev_i32_e32 v163, 31, v162
	v_cndmask_b32_e64 v0, 0, 1, s[30:31]
	v_cmp_ne_u32_e64 s[10:11], 1, v0
	s_andn2_b64 vcc, exec, s[30:31]
	v_lshl_add_u64 v[130:131], v[162:163], 2, s[86:87]
	s_cbranch_vccnz .LBB0_178
	global_load_dword v0, v[130:131], off
	global_load_dword v244, v[130:131], off offset:64
	global_load_dword v245, v[130:131], off offset:128
	global_load_dword v246, v[130:131], off offset:192
	global_load_dword v247, v[130:131], off offset:512
	global_load_dword v248, v[130:131], off offset:576
	global_load_dword v249, v[130:131], off offset:640
	global_load_dword v250, v[130:131], off offset:704
	s_waitcnt vmcnt(0)
	v_mul_f32_e32 v132, v0, v0
	v_cndmask_b32_e64 v0, v0, v132, s[4:5]
	v_cndmask_b32_e64 v132, 0, 1, s[4:5]
	v_cmp_ne_u32_e64 s[8:9], 1, v132
	s_andn2_b64 vcc, exec, s[4:5]
	s_cbranch_vccnz .LBB0_138

.LBB0_140:
	v_mov_b32_e32 v137, v136
	v_mov_b32_e32 v122, v136
	v_mov_b32_e32 v123, v136
	v_pk_mul_f32 v[120:121], v[122:123], v[120:121]
	v_pk_mul_f32 v[122:123], v[122:123], v[116:117]
	v_pk_mul_f32 v[116:117], v[136:137], v[114:115]
	s_and_b64 vcc, exec, s[10:11]
	v_pk_mul_f32 v[118:119], v[136:137], v[118:119]
	v_cvt_pk_bf16_f32 v115, v120, v121
	v_cvt_pk_bf16_f32 v116, v116, v117
	v_cvt_pk_bf16_f32 v117, v122, v123
	s_nop 0
	v_cvt_pk_bf16_f32 v114, v118, v119
	global_store_dwordx4 v[134:135], v[114:117], off offset:256
	s_cbranch_vccnz .LBB0_179
	s_nop 0
	s_nop 1
	v_mov_b32_e32 v0, v244
	s_nop 0
	v_mul_f32_e32 v114, v0, v0
	v_cndmask_b32_e64 v0, v0, v114, s[4:5]
	s_and_b64 vcc, exec, s[8:9]
	s_cbranch_vccnz .LBB0_143

.LBB0_145:
	v_mov_b32_e32 v117, v116
	v_mov_b32_e32 v106, v116
	v_mov_b32_e32 v107, v116
	v_pk_mul_f32 v[104:105], v[106:107], v[104:105]
	v_pk_mul_f32 v[106:107], v[106:107], v[100:101]
	v_pk_mul_f32 v[100:101], v[116:117], v[98:99]
	s_and_b64 vcc, exec, s[10:11]
	v_pk_mul_f32 v[102:103], v[116:117], v[102:103]
	v_cvt_pk_bf16_f32 v99, v104, v105
	v_cvt_pk_bf16_f32 v100, v100, v101
	v_cvt_pk_bf16_f32 v101, v106, v107
	s_nop 0
	v_cvt_pk_bf16_f32 v98, v102, v103
	global_store_dwordx4 v[114:115], v[98:101], off offset:256
	s_cbranch_vccnz .LBB0_180
	s_nop 0
	s_nop 1
	v_mov_b32_e32 v98, v245
	s_nop 0
	v_mul_f32_e32 v99, v98, v98
	v_cndmask_b32_e64 v98, v98, v99, s[4:5]
	s_and_b64 vcc, exec, s[8:9]
	s_cbranch_vccnz .LBB0_148

.LBB0_150:
	v_mov_b32_e32 v101, v100
	v_mov_b32_e32 v90, v100
	v_mov_b32_e32 v91, v100
	v_pk_mul_f32 v[88:89], v[90:91], v[88:89]
	v_pk_mul_f32 v[90:91], v[90:91], v[84:85]
	v_pk_mul_f32 v[84:85], v[100:101], v[82:83]
	s_and_b64 vcc, exec, s[10:11]
	v_pk_mul_f32 v[86:87], v[100:101], v[86:87]
	v_cvt_pk_bf16_f32 v83, v88, v89
	v_cvt_pk_bf16_f32 v84, v84, v85
	v_cvt_pk_bf16_f32 v85, v90, v91
	s_nop 0
	v_cvt_pk_bf16_f32 v82, v86, v87
	global_store_dwordx4 v[98:99], v[82:85], off offset:256
	s_cbranch_vccnz .LBB0_181
	s_nop 0
	s_nop 1
	v_mov_b32_e32 v82, v246
	s_nop 0
	v_mul_f32_e32 v83, v82, v82
	v_cndmask_b32_e64 v82, v82, v83, s[4:5]
	s_and_b64 vcc, exec, s[8:9]
	s_cbranch_vccnz .LBB0_153

.LBB0_155:
	v_mov_b32_e32 v85, v84
	v_mov_b32_e32 v74, v84
	v_mov_b32_e32 v75, v84
	v_pk_mul_f32 v[72:73], v[74:75], v[72:73]
	v_pk_mul_f32 v[74:75], v[74:75], v[68:69]
	v_pk_mul_f32 v[68:69], v[84:85], v[66:67]
	s_and_b64 vcc, exec, s[10:11]
	v_pk_mul_f32 v[70:71], v[84:85], v[70:71]
	v_cvt_pk_bf16_f32 v67, v72, v73
	v_cvt_pk_bf16_f32 v68, v68, v69
	v_cvt_pk_bf16_f32 v69, v74, v75
	s_nop 0
	v_cvt_pk_bf16_f32 v66, v70, v71
	global_store_dwordx4 v[82:83], v[66:69], off offset:256
	s_cbranch_vccnz .LBB0_182
	s_nop 0
	s_nop 1
	v_mov_b32_e32 v0, v247
	s_nop 0
	v_mul_f32_e32 v66, v0, v0
	v_cndmask_b32_e64 v0, v0, v66, s[4:5]
	s_and_b64 vcc, exec, s[8:9]
	s_cbranch_vccnz .LBB0_158

.LBB0_160:
	v_mov_b32_e32 v69, v68
	v_mov_b32_e32 v58, v68
	v_mov_b32_e32 v59, v68
	v_pk_mul_f32 v[56:57], v[58:59], v[56:57]
	v_pk_mul_f32 v[58:59], v[58:59], v[52:53]
	v_pk_mul_f32 v[52:53], v[68:69], v[50:51]
	s_and_b64 vcc, exec, s[10:11]
	v_pk_mul_f32 v[54:55], v[68:69], v[54:55]
	v_cvt_pk_bf16_f32 v51, v56, v57
	v_cvt_pk_bf16_f32 v52, v52, v53
	v_cvt_pk_bf16_f32 v53, v58, v59
	s_nop 0
	v_cvt_pk_bf16_f32 v50, v54, v55
	global_store_dwordx4 v[66:67], v[50:53], off offset:256
	s_cbranch_vccnz .LBB0_183
	s_nop 0
	s_nop 1
	v_mov_b32_e32 v0, v248
	s_nop 0
	v_mul_f32_e32 v50, v0, v0
	v_cndmask_b32_e64 v0, v0, v50, s[4:5]
	s_and_b64 vcc, exec, s[8:9]
	s_cbranch_vccnz .LBB0_163

.LBB0_165:
	v_mov_b32_e32 v53, v52
	v_mov_b32_e32 v42, v52
	v_mov_b32_e32 v43, v52
	v_pk_mul_f32 v[40:41], v[42:43], v[40:41]
	v_pk_mul_f32 v[42:43], v[42:43], v[36:37]
	v_pk_mul_f32 v[36:37], v[52:53], v[34:35]
	s_and_b64 vcc, exec, s[10:11]
	v_pk_mul_f32 v[38:39], v[52:53], v[38:39]
	v_cvt_pk_bf16_f32 v35, v40, v41
	v_cvt_pk_bf16_f32 v36, v36, v37
	v_cvt_pk_bf16_f32 v37, v42, v43
	s_nop 0
	v_cvt_pk_bf16_f32 v34, v38, v39
	global_store_dwordx4 v[50:51], v[34:37], off offset:256
	s_cbranch_vccnz .LBB0_184
	s_nop 0
	s_nop 1
	v_mov_b32_e32 v0, v249
	s_nop 0
	v_mul_f32_e32 v34, v0, v0
	v_cndmask_b32_e64 v0, v0, v34, s[4:5]
	s_and_b64 vcc, exec, s[8:9]
	s_cbranch_vccnz .LBB0_168

.LBB0_170:
	v_mov_b32_e32 v37, v36
	v_mov_b32_e32 v26, v36
	v_mov_b32_e32 v27, v36
	v_pk_mul_f32 v[24:25], v[26:27], v[24:25]
	v_pk_mul_f32 v[26:27], v[26:27], v[20:21]
	v_pk_mul_f32 v[20:21], v[36:37], v[18:19]
	s_and_b64 vcc, exec, s[10:11]
	v_pk_mul_f32 v[22:23], v[36:37], v[22:23]
	v_cvt_pk_bf16_f32 v19, v24, v25
	v_cvt_pk_bf16_f32 v20, v20, v21
	v_cvt_pk_bf16_f32 v21, v26, v27
	s_nop 0
	v_cvt_pk_bf16_f32 v18, v22, v23
	global_store_dwordx4 v[34:35], v[18:21], off offset:256
	s_cbranch_vccnz .LBB0_185
	s_nop 0
	s_nop 1
	v_mov_b32_e32 v0, v250
	s_nop 0
	v_mul_f32_e32 v18, v0, v0
	v_cndmask_b32_e64 v0, v0, v18, s[4:5]
	s_and_b64 vcc, exec, s[8:9]
	s_cbranch_vccnz .LBB0_173
